# attention tile loop: LDS fragment reads software-pipelined (3 buffer sets, counted lgkmcnt); final-norm loop no longer waits for previous row stores
# speedup vs baseline: 1.0036x; 1.0036x over previous
.LBB0_597:
	s_waitcnt vmcnt(5)
	s_waitcnt lgkmcnt(0)
	s_barrier
	v_add_u32_e32 v0, s18, v214
	ds_read_b128 v[2:5], v0
	ds_read_b128 v[6:9], v0 offset:8192
	v_xad_u32 v10, v0, 32, 0
	ds_read_b128 v[244:247], v10
	ds_read_b128 v[248:251], v10 offset:8192
	v_xad_u32 v10, v0, 64, 0
	ds_read_b128 v[12:15], v10
	ds_read_b128 v[224:227], v10 offset:8192
	s_add_i32 s19, s19, 1
	s_cmp_ge_u32 s19, s43
	s_cbranch_scc1 .Lattn_nodma
	s_add_i32 s44, s18, 0xffff6000
	s_cmp_lg_u32 s18, 0
	s_cselect_b32 s44, s44, 0x14000
	s_add_i32 s44, s44, 0
	s_add_i32 s45, s44, s39
	v_lshl_add_u64 v[222:223], s[0:1], 0, v[210:211]
	s_mov_b32 m0, s45
	s_add_i32 s44, s44, s41
	global_load_lds_dwordx4 v[222:223], off
	v_lshl_add_u64 v[222:223], s[0:1], 0, v[212:213]
	s_add_i32 m0, s45, 0x400
	s_nop 0
	global_load_lds_dwordx4 v[222:223], off
	v_lshl_add_u64 v[222:223], s[0:1], 0, v[208:209]
	s_add_i32 m0, s44, 0x4000
	s_nop 0
	global_load_lds_dwordx4 v[222:223], off
	v_lshl_add_u64 v[222:223], s[0:1], 0, v[204:205]
	s_add_i32 m0, s45, 0x6000
	s_nop 0
	global_load_lds_dwordx4 v[222:223], off
	v_lshl_add_u64 v[222:223], s[0:1], 0, v[206:207]
	s_add_i32 m0, s45, 0x6400
	s_nop 0
	global_load_lds_dwordx4 v[222:223], off
.Lattn_nodma:
	s_waitcnt lgkmcnt(4)
	v_mfma_f32_32x32x16_bf16 v[80:95], v[2:5], v[156:159], 0
	v_mfma_f32_32x32x16_bf16 v[96:111], v[6:9], v[156:159], 0
	v_xor_b32_e32 v10, 0x60, v0
	ds_read_b128 v[2:5], v10
	ds_read_b128 v[6:9], v10 offset:8192
	s_waitcnt lgkmcnt(4)
	v_mfma_f32_32x32x16_bf16 v[80:95], v[244:247], v[152:155], v[80:95]
	v_mfma_f32_32x32x16_bf16 v[96:111], v[248:251], v[152:155], v[96:111]
	v_xor_b32_e32 v10, 0x80, v0
	ds_read_b128 v[244:247], v10
	ds_read_b128 v[248:251], v10 offset:8192
	s_waitcnt lgkmcnt(4)
	v_mfma_f32_32x32x16_bf16 v[80:95], v[12:15], v[148:151], v[80:95]
	v_mfma_f32_32x32x16_bf16 v[96:111], v[224:227], v[148:151], v[96:111]
	v_xor_b32_e32 v10, 0xa0, v0
	ds_read_b128 v[12:15], v10
	ds_read_b128 v[224:227], v10 offset:8192
	s_waitcnt lgkmcnt(4)
	v_mfma_f32_32x32x16_bf16 v[80:95], v[2:5], v[144:147], v[80:95]
	v_mfma_f32_32x32x16_bf16 v[96:111], v[6:9], v[144:147], v[96:111]
	v_xor_b32_e32 v10, 0xc0, v0
	ds_read_b128 v[2:5], v10
	ds_read_b128 v[6:9], v10 offset:8192
	s_waitcnt lgkmcnt(4)
	v_mfma_f32_32x32x16_bf16 v[80:95], v[244:247], v[140:143], v[80:95]
	v_mfma_f32_32x32x16_bf16 v[96:111], v[248:251], v[140:143], v[96:111]
	v_xor_b32_e32 v10, 0xe0, v0
	ds_read_b128 v[244:247], v10
	ds_read_b128 v[248:251], v10 offset:8192
	s_waitcnt lgkmcnt(4)
	v_mfma_f32_32x32x16_bf16 v[80:95], v[12:15], v[136:139], v[80:95]
	v_mfma_f32_32x32x16_bf16 v[96:111], v[224:227], v[136:139], v[96:111]
	v_add_u32_e32 v10, s18, v215
	ds_read_b128 v[12:15], v10 offset:16384
	ds_read_b128 v[224:227], v10 offset:20480
	s_waitcnt lgkmcnt(4)
	v_mfma_f32_32x32x16_bf16 v[80:95], v[2:5], v[132:135], v[80:95]
	v_mfma_f32_32x32x16_bf16 v[96:111], v[6:9], v[132:135], v[96:111]
	v_add_u32_e32 v11, s18, v216
	v_xad_u32 v10, v11, 32, 0
	ds_read_b128 v[2:5], v10
	ds_read_b128 v[6:9], v10 offset:4096
	s_waitcnt lgkmcnt(4)
	v_mfma_f32_32x32x16_bf16 v[80:95], v[244:247], v[128:131], v[80:95]
	v_mfma_f32_32x32x16_bf16 v[96:111], v[248:251], v[128:131], v[96:111]
	v_xad_u32 v10, v11, 64, 0
	ds_read_b128 v[244:247], v10
	ds_read_b128 v[248:251], v10 offset:4096
	s_waitcnt lgkmcnt(4)
	v_mfma_f32_32x32x16_bf16 v[80:95], v[12:15], v[124:127], v[80:95]
	v_mfma_f32_32x32x16_bf16 v[96:111], v[224:227], v[124:127], v[96:111]
	v_xor_b32_e32 v10, 0x60, v11
	ds_read_b128 v[12:15], v10
	ds_read_b128 v[224:227], v10 offset:4096
	s_waitcnt lgkmcnt(4)
	v_mfma_f32_32x32x16_bf16 v[80:95], v[2:5], v[120:123], v[80:95]
	v_mfma_f32_32x32x16_bf16 v[96:111], v[6:9], v[120:123], v[96:111]
	v_add_u32_e32 v228, s18, v217
	s_waitcnt lgkmcnt(2)
	v_mfma_f32_32x32x16_bf16 v[80:95], v[244:247], v[116:119], v[80:95]
	v_mfma_f32_32x32x16_bf16 v[96:111], v[248:251], v[116:119], v[96:111]
	ds_read_b128 v[244:247], v228 offset:24576
	ds_read_b128 v[248:251], v228 offset:28672
	s_waitcnt lgkmcnt(2)
	v_mfma_f32_32x32x16_bf16 v[80:95], v[12:15], v[112:115], v[80:95]
	v_mfma_f32_32x32x16_bf16 v[96:111], v[224:227], v[112:115], v[96:111]
	v_add_u32_e32 v229, s18, v218
	v_xad_u32 v243, v229, 32, 0
	v_xad_u32 v252, v229, 64, 0
	v_xor_b32_e32 v253, 0x60, v229
	v_lshl_add_u64 v[204:205], v[204:205], 0, s[76:77]
	v_lshl_add_u64 v[206:207], v[206:207], 0, s[76:77]
	v_lshl_add_u64 v[208:209], v[208:209], 0, s[28:29]
	v_lshl_add_u64 v[210:211], v[210:211], 0, s[52:53]
	v_lshl_add_u64 v[212:213], v[212:213], 0, s[52:53]
	s_nop 3
	v_max_f32_e32 v0, v81, v81
	v_max_f32_e32 v2, v80, v80
	v_max_f32_e32 v0, v2, v0
	v_max3_f32 v0, v0, v82, v83
	v_max3_f32 v0, v0, v84, v85
	v_max3_f32 v0, v0, v86, v87
	v_max3_f32 v0, v0, v88, v89
	v_max3_f32 v0, v0, v90, v91
	v_max3_f32 v0, v0, v92, v93
	v_max3_f32 v0, v0, v94, v95
	v_max3_f32 v0, v0, v96, v97
	v_max3_f32 v0, v0, v98, v99
	v_max3_f32 v0, v0, v100, v101
	v_max3_f32 v0, v0, v102, v103
	v_max3_f32 v0, v0, v104, v105
	v_max3_f32 v0, v0, v106, v107
	v_max3_f32 v0, v0, v108, v109
	v_max3_f32 v0, v0, v110, v111
	ds_bpermute_b32 v2, v219, v0
	s_waitcnt lgkmcnt(0)
	v_max3_f32 v2, v221, v0, v2
	v_sub_f32_e32 v0, v221, v2
	v_exp_f32_e32 v0, v0
	v_cmp_gt_f32_e32 vcc, v2, v221
	s_cbranch_vccz .Lattn_noscale
	v_pk_mul_f32 v[78:79], v[78:79], v[0:1] op_sel_hi:[1,0]
	v_pk_mul_f32 v[76:77], v[76:77], v[0:1] op_sel_hi:[1,0]
	v_pk_mul_f32 v[74:75], v[74:75], v[0:1] op_sel_hi:[1,0]
	v_pk_mul_f32 v[72:73], v[72:73], v[0:1] op_sel_hi:[1,0]
	v_pk_mul_f32 v[70:71], v[70:71], v[0:1] op_sel_hi:[1,0]
	v_pk_mul_f32 v[68:69], v[68:69], v[0:1] op_sel_hi:[1,0]
	v_pk_mul_f32 v[66:67], v[66:67], v[0:1] op_sel_hi:[1,0]
	v_pk_mul_f32 v[64:65], v[64:65], v[0:1] op_sel_hi:[1,0]
	v_pk_mul_f32 v[62:63], v[62:63], v[0:1] op_sel_hi:[1,0]
	v_pk_mul_f32 v[60:61], v[60:61], v[0:1] op_sel_hi:[1,0]
	v_pk_mul_f32 v[58:59], v[58:59], v[0:1] op_sel_hi:[1,0]
	v_pk_mul_f32 v[56:57], v[56:57], v[0:1] op_sel_hi:[1,0]
	v_pk_mul_f32 v[54:55], v[54:55], v[0:1] op_sel_hi:[1,0]
	v_pk_mul_f32 v[52:53], v[52:53], v[0:1] op_sel_hi:[1,0]
	v_pk_mul_f32 v[50:51], v[50:51], v[0:1] op_sel_hi:[1,0]
	v_pk_mul_f32 v[48:49], v[48:49], v[0:1] op_sel_hi:[1,0]
	v_pk_mul_f32 v[46:47], v[46:47], v[0:1] op_sel_hi:[1,0]
	v_pk_mul_f32 v[44:45], v[44:45], v[0:1] op_sel_hi:[1,0]
	v_pk_mul_f32 v[42:43], v[42:43], v[0:1] op_sel_hi:[1,0]
	v_pk_mul_f32 v[40:41], v[40:41], v[0:1] op_sel_hi:[1,0]
	v_pk_mul_f32 v[38:39], v[38:39], v[0:1] op_sel_hi:[1,0]
	v_pk_mul_f32 v[36:37], v[36:37], v[0:1] op_sel_hi:[1,0]
	v_pk_mul_f32 v[34:35], v[34:35], v[0:1] op_sel_hi:[1,0]
	v_pk_mul_f32 v[32:33], v[32:33], v[0:1] op_sel_hi:[1,0]
	v_pk_mul_f32 v[30:31], v[30:31], v[0:1] op_sel_hi:[1,0]
	v_pk_mul_f32 v[28:29], v[28:29], v[0:1] op_sel_hi:[1,0]
	v_pk_mul_f32 v[26:27], v[26:27], v[0:1] op_sel_hi:[1,0]
	v_pk_mul_f32 v[24:25], v[24:25], v[0:1] op_sel_hi:[1,0]
	v_pk_mul_f32 v[22:23], v[22:23], v[0:1] op_sel_hi:[1,0]
	v_pk_mul_f32 v[20:21], v[20:21], v[0:1] op_sel_hi:[1,0]
	v_pk_mul_f32 v[18:19], v[18:19], v[0:1] op_sel_hi:[1,0]
	v_pk_mul_f32 v[16:17], v[16:17], v[0:1] op_sel_hi:[1,0]
.Lattn_noscale:
	v_sub_f32_e32 v222, v80, v2
	v_exp_f32_e32 v80, v222
	v_sub_f32_e32 v223, v96, v2
	v_exp_f32_e32 v96, v223
	v_sub_f32_e32 v222, v81, v2
	v_exp_f32_e32 v81, v222
	v_sub_f32_e32 v223, v97, v2
	v_exp_f32_e32 v97, v223
	v_sub_f32_e32 v222, v82, v2
	v_exp_f32_e32 v82, v222
	v_sub_f32_e32 v223, v98, v2
	v_exp_f32_e32 v98, v223
	v_sub_f32_e32 v222, v83, v2
	v_exp_f32_e32 v83, v222
	v_sub_f32_e32 v223, v99, v2
	v_exp_f32_e32 v99, v223
	v_sub_f32_e32 v222, v84, v2
	v_exp_f32_e32 v84, v222
	v_sub_f32_e32 v223, v100, v2
	v_exp_f32_e32 v100, v223
	v_sub_f32_e32 v222, v85, v2
	v_exp_f32_e32 v85, v222
	v_sub_f32_e32 v223, v101, v2
	v_exp_f32_e32 v101, v223
	v_sub_f32_e32 v222, v86, v2
	v_exp_f32_e32 v86, v222
	v_sub_f32_e32 v223, v102, v2
	v_exp_f32_e32 v102, v223
	v_sub_f32_e32 v222, v87, v2
	v_exp_f32_e32 v87, v222
	v_sub_f32_e32 v223, v103, v2
	v_exp_f32_e32 v103, v223
	v_cvt_pk_bf16_f32 v4, v80, v81
	v_cvt_pk_bf16_f32 v5, v82, v83
	v_cvt_pk_bf16_f32 v6, v84, v85
	v_cvt_pk_bf16_f32 v7, v86, v87
	v_cvt_pk_bf16_f32 v8, v96, v97
	v_cvt_pk_bf16_f32 v9, v98, v99
	v_cvt_pk_bf16_f32 v10, v100, v101
	v_cvt_pk_bf16_f32 v11, v102, v103
	v_add_f32_e32 v80, v80, v96
	v_add_f32_e32 v81, v81, v97
	v_add_f32_e32 v82, v82, v98
	v_add_f32_e32 v83, v83, v99
	v_add_f32_e32 v84, v84, v100
	v_add_f32_e32 v85, v85, v101
	v_add_f32_e32 v86, v86, v102
	v_add_f32_e32 v87, v87, v103
	ds_read_b128 v[96:99], v228 offset:32768
	ds_read_b128 v[100:103], v228 offset:36864
	v_mfma_f32_32x32x16_bf16 v[64:79], v[244:247], v[4:7], v[64:79]
	ds_read_b128 v[244:247], v243
	v_sub_f32_e32 v222, v88, v2
	v_exp_f32_e32 v88, v222
	v_sub_f32_e32 v223, v104, v2
	v_exp_f32_e32 v104, v223
	v_sub_f32_e32 v222, v89, v2
	v_exp_f32_e32 v89, v222
	v_sub_f32_e32 v223, v105, v2
	v_exp_f32_e32 v105, v223
	v_mfma_f32_32x32x16_bf16 v[48:63], v[248:251], v[4:7], v[48:63]
	ds_read_b128 v[248:251], v243 offset:4096
	v_sub_f32_e32 v222, v90, v2
	v_exp_f32_e32 v90, v222
	v_sub_f32_e32 v223, v106, v2
	v_exp_f32_e32 v106, v223
	v_sub_f32_e32 v222, v91, v2
	v_exp_f32_e32 v91, v222
	v_sub_f32_e32 v223, v107, v2
	v_exp_f32_e32 v107, v223
	s_waitcnt lgkmcnt(3)
	v_mfma_f32_32x32x16_bf16 v[32:47], v[96:99], v[4:7], v[32:47]
	ds_read_b128 v[96:99], v243 offset:8192
	v_sub_f32_e32 v222, v92, v2
	v_exp_f32_e32 v92, v222
	v_sub_f32_e32 v223, v108, v2
	v_exp_f32_e32 v108, v223
	v_sub_f32_e32 v222, v93, v2
	v_exp_f32_e32 v93, v222
	v_sub_f32_e32 v223, v109, v2
	v_exp_f32_e32 v109, v223
	s_waitcnt lgkmcnt(3)
	v_mfma_f32_32x32x16_bf16 v[16:31], v[100:103], v[4:7], v[16:31]
	ds_read_b128 v[100:103], v243 offset:12288
	v_sub_f32_e32 v222, v94, v2
	v_exp_f32_e32 v94, v222
	v_sub_f32_e32 v223, v110, v2
	v_exp_f32_e32 v110, v223
	v_sub_f32_e32 v222, v95, v2
	v_exp_f32_e32 v95, v222
	v_sub_f32_e32 v223, v111, v2
	v_exp_f32_e32 v111, v223
	v_cvt_pk_bf16_f32 v12, v88, v89
	v_cvt_pk_bf16_f32 v13, v90, v91
	v_cvt_pk_bf16_f32 v14, v92, v93
	v_cvt_pk_bf16_f32 v15, v94, v95
	v_cvt_pk_bf16_f32 v224, v104, v105
	v_cvt_pk_bf16_f32 v225, v106, v107
	v_cvt_pk_bf16_f32 v226, v108, v109
	v_cvt_pk_bf16_f32 v227, v110, v111
	v_add_f32_e32 v88, v88, v104
	v_add_f32_e32 v89, v89, v105
	v_add_f32_e32 v90, v90, v106
	v_add_f32_e32 v91, v91, v107
	v_add_f32_e32 v92, v92, v108
	v_add_f32_e32 v93, v93, v109
	v_add_f32_e32 v94, v94, v110
	v_add_f32_e32 v95, v95, v111
	v_add_f32_e32 v3, 0, v80
	s_waitcnt lgkmcnt(3)
	v_mfma_f32_32x32x16_bf16 v[64:79], v[244:247], v[12:15], v[64:79]
	ds_read_b128 v[244:247], v252
	v_add_f32_e32 v3, v81, v3
	v_add_f32_e32 v3, v82, v3
	s_waitcnt lgkmcnt(3)
	v_mfma_f32_32x32x16_bf16 v[48:63], v[248:251], v[12:15], v[48:63]
	ds_read_b128 v[248:251], v252 offset:4096
	v_add_f32_e32 v3, v83, v3
	v_add_f32_e32 v3, v84, v3
	s_waitcnt lgkmcnt(3)
	v_mfma_f32_32x32x16_bf16 v[32:47], v[96:99], v[12:15], v[32:47]
	ds_read_b128 v[96:99], v252 offset:8192
	v_add_f32_e32 v3, v85, v3
	v_add_f32_e32 v3, v86, v3
	s_waitcnt lgkmcnt(3)
	v_mfma_f32_32x32x16_bf16 v[16:31], v[100:103], v[12:15], v[16:31]
	ds_read_b128 v[100:103], v252 offset:12288
	v_add_f32_e32 v3, v87, v3
	v_add_f32_e32 v3, v88, v3
	s_waitcnt lgkmcnt(3)
	v_mfma_f32_32x32x16_bf16 v[64:79], v[244:247], v[8:11], v[64:79]
	ds_read_b128 v[244:247], v253
	v_add_f32_e32 v3, v89, v3
	s_waitcnt lgkmcnt(3)
	v_mfma_f32_32x32x16_bf16 v[48:63], v[248:251], v[8:11], v[48:63]
	ds_read_b128 v[248:251], v253 offset:4096
	v_add_f32_e32 v3, v90, v3
	s_waitcnt lgkmcnt(3)
	v_mfma_f32_32x32x16_bf16 v[32:47], v[96:99], v[8:11], v[32:47]
	ds_read_b128 v[96:99], v253 offset:8192
	v_add_f32_e32 v3, v91, v3
	s_waitcnt lgkmcnt(3)
	v_mfma_f32_32x32x16_bf16 v[16:31], v[100:103], v[8:11], v[16:31]
	ds_read_b128 v[100:103], v253 offset:12288
	v_add_f32_e32 v3, v92, v3
	s_waitcnt lgkmcnt(3)
	v_mfma_f32_32x32x16_bf16 v[64:79], v[244:247], v[224:227], v[64:79]
	v_add_f32_e32 v3, v93, v3
	s_waitcnt lgkmcnt(2)
	v_mfma_f32_32x32x16_bf16 v[48:63], v[248:251], v[224:227], v[48:63]
	v_add_f32_e32 v3, v94, v3
	s_waitcnt lgkmcnt(1)
	v_mfma_f32_32x32x16_bf16 v[32:47], v[96:99], v[224:227], v[32:47]
	v_add_f32_e32 v3, v95, v3
	s_waitcnt lgkmcnt(0)
	v_mfma_f32_32x32x16_bf16 v[16:31], v[100:103], v[224:227], v[16:31]
	v_fmac_f32_e32 v3, v220, v0
	s_add_i32 s44, s18, 0xa000
	s_cmp_lg_u32 s18, 0x14000
	s_cselect_b32 s18, s44, 0
	s_cmp_eq_u32 s43, s19
	s_cbranch_scc1 .LBB0_603
	v_mov_b32_e32 v221, v2
	v_mov_b32_e32 v220, v3
	s_branch .LBB0_597

.LBB0_1724:
	s_cmp_ge_i32 s11, s58
	s_cselect_b64 s[0:1], -1, 0
	s_cmp_lt_i32 s11, s59
	s_cselect_b64 s[2:3], -1, 0
	s_and_b64 s[0:1], s[0:1], s[2:3]
	s_andn2_b64 vcc, exec, s[0:1]
	s_cbranch_vccnz .LBB0_1796
	v_readlane_b32 s16, v254, 0
	v_readlane_b32 s17, v254, 1
	s_lshl_b32 s0, s39, 3
	v_ashrrev_i32_e32 v32, 6, v179
	v_add_u32_e32 v48, s0, v32
	s_movk_i32 s18, 0x5000
	v_cmp_gt_i32_e32 vcc, s18, v48
	s_and_saveexec_b64 s[2:3], vcc
	s_cbranch_execz .LBB0_1730
	s_waitcnt lgkmcnt(0)
	s_load_dwordx4 s[40:43], s[16:17], 0xe0
	v_lshlrev_b32_e32 v33, 2, v179
	v_ashrrev_i32_e32 v49, 31, v48
	v_and_b32_e32 v0, 0xfc, v33
	v_lshlrev_b64 v[18:19], 12, v[48:49]
	v_mov_b32_e32 v17, 0
	v_lshlrev_b32_e32 v16, 2, v0
	s_waitcnt lgkmcnt(0)
	v_lshl_add_u64 v[18:19], s[42:43], 0, v[18:19]
	global_load_dwordx4 v[0:3], v16, s[40:41]
	global_load_dwordx4 v[4:7], v16, s[40:41] offset:1024
	global_load_dwordx4 v[8:11], v16, s[40:41] offset:2048
	global_load_dwordx4 v[12:15], v16, s[40:41] offset:3072
	v_lshl_add_u64 v[16:17], v[18:19], 0, v[16:17]
	global_load_dwordx4 v[28:31], v[16:17], off
	global_load_dwordx4 v[24:27], v[16:17], off offset:1024
	global_load_dwordx4 v[20:23], v[16:17], off offset:2048
	s_nop 0
	global_load_dwordx4 v[16:19], v[16:17], off offset:3072
	v_bfrev_b32_e32 v34, 0.5
	s_movk_i32 s1, 0x80
	v_bitop3_b32 v49, v33, 4, v34 bitop3:0x6c
	v_bitop3_b32 v54, v33, 8, v34 bitop3:0x6c
	v_bitop3_b32 v55, v33, 16, v34 bitop3:0x6c
	v_bitop3_b32 v56, v33, 32, v34 bitop3:0x6c
	v_bitop3_b32 v57, v33, 64, v34 bitop3:0x6c
	v_bitop3_b32 v58, v33, s1, v34 bitop3:0x6c
	v_ashrrev_i32_e32 v33, 31, v32
	s_ashr_i32 s1, s0, 31
	v_lshl_add_u64 v[32:33], v[32:33], 0, s[0:1]
	v_lshlrev_b64 v[32:33], 12, v[32:33]
	v_and_b32_e32 v34, 63, v179
	v_lshl_or_b32 v32, v34, 4, v32
	v_lshl_add_u64 v[50:51], s[42:43], 0, v[32:33]
	s_mov_b64 s[14:15], 0
	v_mov_b32_e32 v59, 0x358637bd
	s_mov_b32 s19, 0x800000
	s_waitcnt vmcnt(0)
	s_branch .LBB0_1728

.LBB0_1728:
	v_readlane_b32 s0, v255, 15
	s_movk_i32 s16, 0x4fff
	v_readlane_b32 s1, v255, 16
	v_add_u32_e32 v48, s0, v48
	v_cmp_lt_i32_e32 vcc, s16, v48
	v_readlane_b32 s16, v255, 29
	v_readlane_b32 s17, v255, 30
	v_cmp_gt_i32_e64 s[0:1], s18, v48
	s_waitcnt vmcnt(4)
	v_mov_b32_e32 v32, v28
	v_lshl_add_u64 v[52:53], v[50:51], 0, s[16:17]
	v_mov_b32_e32 v33, v29
	v_mov_b32_e32 v34, v30
	v_mov_b32_e32 v35, v31
	v_mov_b32_e32 v36, v24
	v_mov_b32_e32 v37, v25
	v_mov_b32_e32 v38, v26
	v_mov_b32_e32 v39, v27
	v_mov_b32_e32 v40, v20
	v_mov_b32_e32 v41, v21
	v_mov_b32_e32 v42, v22
	v_mov_b32_e32 v43, v23
	v_mov_b32_e32 v44, v16
	v_mov_b32_e32 v45, v17
	v_mov_b32_e32 v46, v18
	v_mov_b32_e32 v47, v19
	s_and_saveexec_b64 s[16:17], s[0:1]
	s_cbranch_execz .LBB0_1727
	v_readlane_b32 s0, v255, 29
	v_readlane_b32 s1, v255, 30
	s_nop 1
	v_lshl_add_u64 v[44:45], v[50:51], 0, s[0:1]
	global_load_dwordx4 v[32:35], v[44:45], off
	global_load_dwordx4 v[36:39], v[44:45], off offset:1024
	global_load_dwordx4 v[40:43], v[44:45], off offset:2048
	s_nop 0
	global_load_dwordx4 v[44:47], v[44:45], off offset:3072
	s_branch .LBB0_1727
